# grid barrier: XCD leader signals its XCD generation before (not after) its own L1/L2 invalidate; non-leaders still acquire themselves
# baseline (speedup 1.0000x reference)
.LBB0_61:
	s_or_b64 exec, exec, s[4:5]
	s_mov_b64 s[4:5], exec
	v_mbcnt_lo_u32_b32 v0, s4, 0
	v_mbcnt_hi_u32_b32 v0, s5, v0
	v_cmp_eq_u32_e32 vcc, 0, v0
	s_waitcnt vmcnt(0)
	s_and_saveexec_b64 s[6:7], vcc
	s_cbranch_execz .LBB0_63
	s_bcnt1_i32_b64 s0, s[4:5]
	v_mov_b32_e32 v0, s0
	v_readlane_b32 s0, v253, 14
	v_readlane_b32 s1, v253, 15
	s_nop 4
	global_atomic_add v177, v0, s[0:1]
.LBB0_63:
	s_or_b64 exec, exec, s[6:7]
	buffer_inv sc1
	s_waitcnt vmcnt(0)
